# phase 9 row loop: next row's loads issued one row ahead into spare registers (on top of the de-serialised chunk loads and hoisted gains)
# speedup vs baseline: 1.0076x; 1.0005x over previous
; DI float bflo(unsigned u) { return __uint_as_float(u << 16); }
; DI float bfhi(unsigned u) { return __uint_as_float(u & 0xffff0000u); }
; DI void phase9(const Params& p) {
;     const int lane = VTID & 63, w = VTID >> 6;
;     const float* x = p.in[0]; const float* g1 = p.in[15]; const float* g2 = p.in[20];
;     const bf16_t* MIX = (const bf16_t*)(p.ws + OFF_MIX);
;     const bf16_t* F = (const bf16_t*)(p.ws + OFF_O);
;     const float* RSTD = (const float*)(p.ws + OFF_GATES);
;     for (int row = VBLK * 4 + w; row < T; row += VGRID * 4) {
;         f32x4 fv[4], mv[4]; float ss = 0.f;
; #pragma unroll
;         for (int i = 0; i < 4; ++i) {
;             const u32x2 u = *(const u32x2*)(F + (size_t)row * 1024 + i * 256 + lane * 4);
;             fv[i][0] = bflo(u.x); fv[i][1] = bfhi(u.x); fv[i][2] = bflo(u.y); fv[i][3] = bfhi(u.y);
;             const u32x2 um = *(const u32x2*)(MIX + (size_t)row * 1024 + i * 256 + lane * 4);
;             mv[i][0] = bflo(um.x); mv[i][1] = bfhi(um.x); mv[i][2] = bflo(um.y); mv[i][3] = bfhi(um.y);
;             ss += fv[i][0] * fv[i][0] + fv[i][1] * fv[i][1] + fv[i][2] * fv[i][2] + fv[i][3] * fv[i][3];
;         }
.LBB0_904:
	s_cmp_gt_i32 s90, 9
	s_cselect_b64 s[0:1], -1, 0
	s_cmp_lt_i32 s91, 10
	s_cselect_b64 s[2:3], -1, 0
	s_or_b64 s[0:1], s[0:1], s[2:3]
	s_and_b64 vcc, exec, s[0:1]
	s_cbranch_vccnz .LBB0_958
	v_and_b32_e32 v14, 0x3ff, v0
	v_readlane_b32 s0, v238, 0
	v_bfe_u32 v0, v14, 6, 2
	s_lshl_b32 s0, s0, 3
	v_or3_b32 v0, v150, s0, v0
	s_mov_b32 s0, 0x8000
	v_cmp_gt_i32_e32 vcc, s0, v0
	s_and_saveexec_b64 s[0:1], vcc
	v_readlane_b32 s16, v238, 15
	v_readlane_b32 s17, v238, 16
	v_readlane_b32 s18, v238, 17
	v_readlane_b32 s19, v238, 18
	v_readlane_b32 s20, v238, 19
	v_readlane_b32 s21, v238, 20
	v_readlane_b32 s22, v238, 21
	v_readlane_b32 s23, v238, 22
	v_readlane_b32 s24, v238, 23
	v_readlane_b32 s25, v238, 24
	v_readlane_b32 s26, v238, 25
	v_readlane_b32 s27, v238, 26
	v_readlane_b32 s28, v238, 27
	v_readlane_b32 s29, v238, 28
	v_readlane_b32 s30, v238, 29
	v_readlane_b32 s31, v238, 30
	s_cbranch_execz .LBB0_908
	v_mbcnt_lo_u32_b32 v1, -1, 0
	v_mbcnt_hi_u32_b32 v1, -1, v1
	v_and_b32_e32 v3, 64, v1
	v_xor_b32_e32 v2, 32, v1
	v_add_u32_e32 v3, 64, v3
	v_cmp_lt_i32_e32 vcc, v2, v3
	v_readlane_b32 s2, v238, 10
	v_readlane_b32 s36, v238, 31
	v_cndmask_b32_e32 v2, v1, v2, vcc
	v_lshlrev_b32_e32 v15, 2, v2
	v_xor_b32_e32 v2, 16, v1
	v_cmp_lt_i32_e32 vcc, v2, v3
	v_readlane_b32 s3, v238, 11
	s_lshl_b32 s2, s2, 3
	v_cndmask_b32_e32 v2, v1, v2, vcc
	v_lshlrev_b32_e32 v16, 2, v2
	v_xor_b32_e32 v2, 8, v1
	v_cmp_lt_i32_e32 vcc, v2, v3
	v_mov_b32_e32 v5, 0
	v_readlane_b32 s50, v238, 45
	v_cndmask_b32_e32 v2, v1, v2, vcc
	v_lshlrev_b32_e32 v17, 2, v2
	v_xor_b32_e32 v2, 4, v1
	v_cmp_lt_i32_e32 vcc, v2, v3
	v_readlane_b32 s51, v238, 46
	v_mov_b64_e32 v[6:7], 0x18ba5800
	v_cndmask_b32_e32 v2, v1, v2, vcc
	v_lshlrev_b32_e32 v18, 2, v2
	v_xor_b32_e32 v2, 2, v1
	v_cmp_lt_i32_e32 vcc, v2, v3
	s_ashr_i32 s3, s2, 31
	v_and_b32_e32 v12, 63, v14
	v_cndmask_b32_e32 v2, v1, v2, vcc
	v_lshlrev_b32_e32 v19, 2, v2
	v_xor_b32_e32 v2, 1, v1
	v_cmp_lt_i32_e32 vcc, v2, v3
	s_lshl_b64 s[4:5], s[2:3], 2
	s_lshl_b64 s[6:7], s[2:3], 12
	v_cndmask_b32_e32 v1, v1, v2, vcc
	v_lshlrev_b32_e32 v20, 2, v1
	v_lshlrev_b32_e32 v1, 4, v14
	v_and_b32_e32 v4, 0x3f0, v1
	v_ashrrev_i32_e32 v1, 31, v0
	v_lshlrev_b64 v[8:9], 12, v[0:1]
	v_lshlrev_b64 v[10:11], 11, v[0:1]
	v_lshl_add_u64 v[2:3], s[50:51], 0, v[4:5]
	v_lshl_add_u64 v[4:5], s[84:85], 0, v[4:5]
	v_lshl_add_u64 v[6:7], v[0:1], 2, v[6:7]
	v_lshl_or_b32 v8, v12, 4, v8
	v_lshl_or_b32 v10, v12, 3, v10
	s_lshl_b64 s[8:9], s[2:3], 11
	s_mov_b64 s[10:11], 0
	v_mov_b32_e32 v1, 0x358637bd
	s_mov_b32 s3, 0x800000
	s_movk_i32 s12, 0x7fff
	v_readlane_b32 s37, v238, 32
	v_readlane_b32 s38, v238, 33
	v_readlane_b32 s39, v238, 34
	v_readlane_b32 s40, v238, 35
	v_readlane_b32 s41, v238, 36
	v_readlane_b32 s42, v238, 37
	v_readlane_b32 s43, v238, 38
	v_readlane_b32 s44, v238, 39
	v_readlane_b32 s45, v238, 40
	v_readlane_b32 s46, v238, 41
	v_readlane_b32 s47, v238, 42
	v_readlane_b32 s48, v238, 43
	v_readlane_b32 s49, v238, 44
	global_load_dwordx4 v[200:203], v[2:3], off
	global_load_dwordx4 v[204:207], v[2:3], off offset:1024
	global_load_dwordx4 v[208:211], v[2:3], off offset:2048
	global_load_dwordx4 v[212:215], v[2:3], off offset:3072
	global_load_dwordx4 v[216:219], v[4:5], off
	global_load_dwordx4 v[220:223], v[4:5], off offset:1024
	global_load_dwordx4 v[224:227], v[4:5], off offset:2048
	global_load_dwordx4 v[228:231], v[4:5], off offset:3072
	s_waitcnt vmcnt(0)
	v_lshl_add_u64 v[140:141], s[88:89], 0, v[10:11]
	v_add_co_u32_e32 v138, vcc, 0x5ba5000, v140
	v_lshl_add_u64 v[136:137], s[88:89], 0, v[6:7]
	s_nop 0
	v_addc_co_u32_e32 v139, vcc, 0, v141, vcc
	v_lshl_add_u64 v[142:143], s[16:17], 0, v[8:9]
	v_add_co_u32_e32 v140, vcc, 0x9ba5000, v140
	s_nop 1
	v_addc_co_u32_e32 v141, vcc, 0, v141, vcc
	global_load_dword v100, v[136:137], off
	global_load_dwordx2 v[102:103], v[138:139], off offset:2048
	global_load_dwordx2 v[104:105], v[138:139], off offset:2560
	global_load_dwordx2 v[106:107], v[138:139], off offset:3072
	global_load_dwordx2 v[108:109], v[138:139], off offset:3584
	global_load_dwordx2 v[110:111], v[140:141], off offset:2048
	global_load_dwordx2 v[112:113], v[140:141], off offset:2560
	global_load_dwordx2 v[114:115], v[140:141], off offset:3072
	global_load_dwordx2 v[116:117], v[140:141], off offset:3584
	global_load_dwordx4 v[120:123], v[142:143], off
	global_load_dwordx4 v[124:127], v[142:143], off offset:1024
	global_load_dwordx4 v[128:131], v[142:143], off offset:2048
	global_load_dwordx4 v[132:135], v[142:143], off offset:3072
	s_waitcnt vmcnt(0)
	s_branch .Lp9_in

; DI float bflo(unsigned u) { return __uint_as_float(u << 16); }
; DI float bfhi(unsigned u) { return __uint_as_float(u & 0xffff0000u); }
; DI void phase9(const Params& p) {
;     ...
;     for (int row = VBLK * 4 + w; row < T; row += VGRID * 4) {
;         f32x4 fv[4], mv[4]; float ss = 0.f;
; #pragma unroll
;         for (int i = 0; i < 4; ++i) {
;             const u32x2 u = *(const u32x2*)(F + (size_t)row * 1024 + i * 256 + lane * 4);
;             fv[i][0] = bflo(u.x); fv[i][1] = bfhi(u.x); fv[i][2] = bflo(u.y); fv[i][3] = bfhi(u.y);
;             const u32x2 um = *(const u32x2*)(MIX + (size_t)row * 1024 + i * 256 + lane * 4);
;             mv[i][0] = bflo(um.x); mv[i][1] = bfhi(um.x); mv[i][2] = bflo(um.y); mv[i][3] = bfhi(um.y);
;             ss += fv[i][0] * fv[i][0] + fv[i][1] * fv[i][1] + fv[i][2] * fv[i][2] + fv[i][3] * fv[i][3];
;         }
.Lp9_in:
	v_lshl_add_u64 v[12:13], s[86:87], 0, v[8:9]
	v_mov_b32_e32 v42, v100
	v_mov_b32_e32 v36, v102
	v_mov_b32_e32 v37, v103
	v_mov_b32_e32 v44, v104
	v_mov_b32_e32 v45, v105
	v_mov_b32_e32 v46, v106
	v_mov_b32_e32 v47, v107
	v_mov_b32_e32 v48, v108
	v_mov_b32_e32 v49, v109
	v_mov_b32_e32 v40, v110
	v_mov_b32_e32 v41, v111
	v_mov_b32_e32 v50, v112
	v_mov_b32_e32 v51, v113
	v_mov_b32_e32 v52, v114
	v_mov_b32_e32 v53, v115
	v_mov_b32_e32 v54, v116
	v_mov_b32_e32 v55, v117
	v_mov_b32_e32 v30, v120
	v_mov_b32_e32 v31, v121
	v_mov_b32_e32 v32, v122
	v_mov_b32_e32 v33, v123
	v_mov_b32_e32 v80, v124
	v_mov_b32_e32 v81, v125
	v_mov_b32_e32 v82, v126
	v_mov_b32_e32 v83, v127
	v_mov_b32_e32 v84, v128
	v_mov_b32_e32 v85, v129
	v_mov_b32_e32 v86, v130
	v_mov_b32_e32 v87, v131
	v_mov_b32_e32 v88, v132
	v_mov_b32_e32 v89, v133
	v_mov_b32_e32 v90, v134
	v_mov_b32_e32 v91, v135
	v_add_u32_e32 v0, s2, v0
	v_lshl_add_u64 v[6:7], v[6:7], 0, s[4:5]
	v_lshl_add_u64 v[8:9], v[8:9], 0, s[6:7]
	v_lshl_add_u64 v[10:11], v[10:11], 0, s[8:9]
	v_cmp_ge_i32_e32 vcc, s12, v0
	s_and_saveexec_b64 s[98:99], vcc
	s_cbranch_execz .Lp9_nopf
	v_lshl_add_u64 v[140:141], s[88:89], 0, v[10:11]
	v_add_co_u32_e32 v138, vcc, 0x5ba5000, v140
	v_lshl_add_u64 v[136:137], s[88:89], 0, v[6:7]
	s_nop 0
	v_addc_co_u32_e32 v139, vcc, 0, v141, vcc
	v_lshl_add_u64 v[142:143], s[16:17], 0, v[8:9]
	v_add_co_u32_e32 v140, vcc, 0x9ba5000, v140
	s_nop 1
	v_addc_co_u32_e32 v141, vcc, 0, v141, vcc
	global_load_dword v100, v[136:137], off
	global_load_dwordx2 v[102:103], v[138:139], off offset:2048
	global_load_dwordx2 v[104:105], v[138:139], off offset:2560
	global_load_dwordx2 v[106:107], v[138:139], off offset:3072
	global_load_dwordx2 v[108:109], v[138:139], off offset:3584
	global_load_dwordx2 v[110:111], v[140:141], off offset:2048
	global_load_dwordx2 v[112:113], v[140:141], off offset:2560
	global_load_dwordx2 v[114:115], v[140:141], off offset:3072
	global_load_dwordx2 v[116:117], v[140:141], off offset:3584
	global_load_dwordx4 v[120:123], v[142:143], off
	global_load_dwordx4 v[124:127], v[142:143], off offset:1024
	global_load_dwordx4 v[128:131], v[142:143], off offset:2048
	global_load_dwordx4 v[132:135], v[142:143], off offset:3072
; DI float bflo(unsigned u) { return __uint_as_float(u << 16); }
; DI float bfhi(unsigned u) { return __uint_as_float(u & 0xffff0000u); }
; DI void phase9(const Params& p) {
;     ...
;         for (int i = 0; i < 4; ++i) {
;             const u32x2 u = *(const u32x2*)(F + (size_t)row * 1024 + i * 256 + lane * 4);
;             fv[i][0] = bflo(u.x); fv[i][1] = bfhi(u.x); fv[i][2] = bflo(u.y); fv[i][3] = bfhi(u.y);
;             const u32x2 um = *(const u32x2*)(MIX + (size_t)row * 1024 + i * 256 + lane * 4);
;             mv[i][0] = bflo(um.x); mv[i][1] = bfhi(um.x); mv[i][2] = bflo(um.y); mv[i][3] = bfhi(um.y);
;             ss += fv[i][0] * fv[i][0] + fv[i][1] * fv[i][1] + fv[i][2] * fv[i][2] + fv[i][3] * fv[i][3];
;         }
;         ss = wave_sum(ss);
;         const float rstd = rsqrtf(ss * (1.f / 1024.f) + NORM_EPS);
;         const float rstd1 = RSTD[row];
; #pragma unroll
;         for (int i = 0; i < 4; ++i) {
;             const f32x4 ga = *(const f32x4*)(g1 + i * 256 + lane * 4);
;             const f32x4 gb = *(const f32x4*)(g2 + i * 256 + lane * 4);
;             f32x4 xv = *(const f32x4*)(x + (size_t)row * 1024 + i * 256 + lane * 4);
; #pragma unroll
;             for (int e = 0; e < 4; ++e) { xv[e] += mv[i][e] * rstd1 * ga[e]; xv[e] += fv[i][e] * rstd * gb[e]; }
;             *(f32x4*)(p.out + (size_t)row * 1024 + i * 256 + lane * 4) = xv;
;         }
.Lp9_nopf:
	s_or_b64 exec, exec, s[98:99]
	v_and_b32_e32 v35, 0xffff0000, v36
	v_and_b32_e32 v57, 0xffff0000, v44
	v_lshlrev_b32_e32 v34, 16, v36
	v_lshlrev_b32_e32 v56, 16, v44
	v_and_b32_e32 v59, 0xffff0000, v46
	v_and_b32_e32 v61, 0xffff0000, v48
	v_lshlrev_b32_e32 v62, 16, v40
	v_and_b32_e32 v63, 0xffff0000, v40
	v_mov_b32_e32 v66, v35
	v_mov_b32_e32 v67, v57
	v_lshlrev_b32_e32 v36, 16, v37
	v_lshlrev_b32_e32 v44, 16, v45
	v_lshlrev_b32_e32 v58, 16, v46
	v_lshlrev_b32_e32 v60, 16, v48
	v_lshlrev_b32_e32 v40, 16, v41
	v_and_b32_e32 v41, 0xffff0000, v41
	v_mov_b32_e32 v64, v34
	v_mov_b32_e32 v65, v56
	v_mov_b32_e32 v74, v59
	v_mov_b32_e32 v75, v61
	v_pk_mul_f32 v[62:63], v[42:43], v[62:63] op_sel_hi:[0,1]
	v_pk_mul_f32 v[66:67], v[66:67], v[66:67]
	v_and_b32_e32 v37, 0xffff0000, v37
	v_and_b32_e32 v45, 0xffff0000, v45
	v_lshlrev_b32_e32 v46, 16, v47
	v_lshlrev_b32_e32 v48, 16, v49
	v_mov_b32_e32 v68, v36
	v_mov_b32_e32 v69, v44
	v_mov_b32_e32 v72, v58
	v_mov_b32_e32 v73, v60
	v_pk_mul_f32 v[40:41], v[42:43], v[40:41] op_sel_hi:[0,1]
	v_pk_mul_f32 v[74:75], v[74:75], v[74:75]
	v_pk_fma_f32 v[22:23], v[62:63], v[200:201], v[30:31]
	v_pk_fma_f32 v[30:31], v[64:65], v[64:65], v[66:67]
	v_and_b32_e32 v47, 0xffff0000, v47
	v_and_b32_e32 v49, 0xffff0000, v49
	v_mov_b32_e32 v70, v37
	v_mov_b32_e32 v71, v45
	v_mov_b32_e32 v76, v46
	v_mov_b32_e32 v77, v48
	v_pk_fma_f32 v[24:25], v[40:41], v[202:203], v[32:33]
	v_pk_fma_f32 v[32:33], v[72:73], v[72:73], v[74:75]
	v_pk_fma_f32 v[30:31], v[68:69], v[68:69], v[30:31]
	v_mov_b32_e32 v78, v47
	v_mov_b32_e32 v79, v49
	v_pk_fma_f32 v[32:33], v[76:77], v[76:77], v[32:33]
	v_pk_fma_f32 v[30:31], v[70:71], v[70:71], v[30:31]
	v_pk_fma_f32 v[32:33], v[78:79], v[78:79], v[32:33]
	v_add_f32_e32 v21, v30, v31
	v_add_f32_e32 v21, v21, v32
	v_add_f32_e32 v21, v21, v33
	ds_bpermute_b32 v30, v15, v21
	s_waitcnt lgkmcnt(0)
	v_add_f32_e32 v21, v21, v30
	ds_bpermute_b32 v30, v16, v21
	s_waitcnt lgkmcnt(0)
	v_add_f32_e32 v21, v21, v30
	ds_bpermute_b32 v30, v17, v21
	s_waitcnt lgkmcnt(0)
	v_add_f32_e32 v21, v21, v30
	ds_bpermute_b32 v30, v18, v21
	s_waitcnt lgkmcnt(0)
	v_add_f32_e32 v21, v21, v30
	ds_bpermute_b32 v30, v19, v21
	s_waitcnt lgkmcnt(0)
	v_add_f32_e32 v21, v21, v30
	ds_bpermute_b32 v30, v20, v21
	s_waitcnt lgkmcnt(0)
	v_add_f32_e32 v21, v21, v30
	v_fmamk_f32 v21, v21, 0x3a800000, v1
	v_mul_f32_e32 v30, 0x4b800000, v21
	v_cmp_gt_f32_e32 vcc, s3, v21
	s_nop 1
	v_cndmask_b32_e32 v21, v21, v30, vcc
	v_rsq_f32_e32 v21, v21
	s_nop 0
	v_mul_f32_e32 v30, 0x45800000, v21
	v_cndmask_b32_e32 v40, v21, v30, vcc
	v_pk_mul_f32 v[30:31], v[40:41], v[34:35] op_sel_hi:[0,1]
	v_pk_mul_f32 v[32:33], v[40:41], v[36:37] op_sel_hi:[0,1]
	v_pk_fma_f32 v[22:23], v[216:217], v[30:31], v[22:23]
	v_pk_fma_f32 v[24:25], v[218:219], v[32:33], v[24:25]
	global_store_dwordx4 v[12:13], v[22:25], off
	v_lshlrev_b32_e32 v34, 16, v50
	v_and_b32_e32 v35, 0xffff0000, v50
	v_lshlrev_b32_e32 v36, 16, v51
	v_and_b32_e32 v37, 0xffff0000, v51
	v_pk_mul_f32 v[34:35], v[42:43], v[34:35] op_sel_hi:[0,1]
	v_pk_mul_f32 v[36:37], v[42:43], v[36:37] op_sel_hi:[0,1]
	v_pk_mul_f32 v[50:51], v[40:41], v[56:57] op_sel_hi:[0,1]
	v_pk_mul_f32 v[44:45], v[40:41], v[44:45] op_sel_hi:[0,1]
	v_pk_mul_f32 v[46:47], v[40:41], v[46:47] op_sel_hi:[0,1]
	v_cmp_lt_i32_e32 vcc, s12, v0
	s_or_b64 s[10:11], vcc, s[10:11]
	v_pk_fma_f32 v[22:23], v[34:35], v[204:205], v[80:81]
	v_pk_fma_f32 v[24:25], v[36:37], v[206:207], v[82:83]
	v_pk_fma_f32 v[22:23], v[220:221], v[50:51], v[22:23]
	v_pk_fma_f32 v[24:25], v[222:223], v[44:45], v[24:25]
	global_store_dwordx4 v[12:13], v[22:25], off offset:1024
	v_lshlrev_b32_e32 v34, 16, v52
	v_and_b32_e32 v35, 0xffff0000, v52
	v_lshlrev_b32_e32 v36, 16, v53
	v_and_b32_e32 v37, 0xffff0000, v53
	v_pk_mul_f32 v[34:35], v[42:43], v[34:35] op_sel_hi:[0,1]
	v_pk_mul_f32 v[36:37], v[42:43], v[36:37] op_sel_hi:[0,1]
	v_pk_mul_f32 v[44:45], v[40:41], v[58:59] op_sel_hi:[0,1]
	v_pk_fma_f32 v[22:23], v[34:35], v[208:209], v[84:85]
	v_pk_fma_f32 v[24:25], v[36:37], v[210:211], v[86:87]
	v_pk_fma_f32 v[22:23], v[224:225], v[44:45], v[22:23]
	v_pk_fma_f32 v[24:25], v[226:227], v[46:47], v[24:25]
	global_store_dwordx4 v[12:13], v[22:25], off offset:2048
	v_lshlrev_b32_e32 v34, 16, v54
	v_and_b32_e32 v35, 0xffff0000, v54
	v_lshlrev_b32_e32 v36, 16, v55
	v_and_b32_e32 v37, 0xffff0000, v55
	v_pk_mul_f32 v[34:35], v[42:43], v[34:35] op_sel_hi:[0,1]
	v_pk_mul_f32 v[36:37], v[42:43], v[36:37] op_sel_hi:[0,1]
	v_pk_mul_f32 v[38:39], v[40:41], v[60:61] op_sel_hi:[0,1]
	v_pk_mul_f32 v[40:41], v[40:41], v[48:49] op_sel_hi:[0,1]
	v_pk_fma_f32 v[22:23], v[34:35], v[212:213], v[88:89]
	v_pk_fma_f32 v[24:25], v[36:37], v[214:215], v[90:91]
	v_pk_fma_f32 v[22:23], v[38:39], v[228:229], v[22:23]
	v_pk_fma_f32 v[24:25], v[40:41], v[230:231], v[24:25]
	global_store_dwordx4 v[12:13], v[22:25], off offset:3072
	s_andn2_b64 exec, exec, s[10:11]
	s_cbranch_execnz .LBB0_907
